# grid barrier: the first workgroup of each XCD to arrive starts one early L2 write-back (leader's write-back finds most lines clean)
# baseline (speedup 1.0000x reference)
; __device__ __forceinline__ unsigned xb_ld(unsigned* p)              { return __hip_atomic_load(p, __ATOMIC_RELAXED, __HIP_MEMORY_SCOPE_AGENT); }
; __device__ __forceinline__ unsigned xb_add(unsigned* p, unsigned v) { return __hip_atomic_fetch_add(p, v, __ATOMIC_RELAXED, __HIP_MEMORY_SCOPE_AGENT); }
; #define XB_SPIN(cond, bar) do { unsigned _sp = 0; while (cond) { __builtin_amdgcn_s_sleep(1); \
;     if ((++_sp & 255u) == 0u) { if (xb_ld(&(bar)[XB_TMO])) break; if (_sp > XB_SPIN_CAP) { atomicAdd(&(bar)[XB_TMO], 1u); break; } } } } while (0)
; __device__ __forceinline__ void xcd_barrier(const XcdBarrier& b) {
;     ...
;         unsigned nloc = b.st[0], nx = b.st[1];
;         if (nloc == 0u) { xcd_barrier_complete(bar, b.x, nloc, nx); b.st[0] = nloc; b.st[1] = nx; }
;         const unsigned old = xb_add(&bar[XB_XSUB(b.x)], 1u);
;         const unsigned gen = old / nloc;
;         if (old + 1u == (gen + 1u) * nloc) {
;             __builtin_amdgcn_fence(__ATOMIC_RELEASE, "agent");
;             asm volatile("s_waitcnt vmcnt(0)" ::: "memory");
;             const unsigned og = xb_add(&bar[XB_TOP], 1u);
;             const unsigned tg = og / nx;
;             if (og + 1u == (tg + 1u) * nx) xb_add(&bar[XB_TOPGEN], 1u);
;             else XB_SPIN(xb_ld(&bar[XB_TOPGEN]) == tg, bar);
;             __builtin_amdgcn_fence(__ATOMIC_ACQUIRE, "agent");
;             xb_add(&bar[XB_XGEN(b.x)], 1u);
;             asm volatile("s_waitcnt vmcnt(0)" ::: "memory");
;         } else {
;             XB_SPIN(xb_ld(&bar[XB_XGEN(b.x)]) == gen, bar);
;             __builtin_amdgcn_fence(__ATOMIC_ACQUIRE, "agent");
;             asm volatile("s_waitcnt vmcnt(0)" ::: "memory");
;         }
.LBB0_1091:
	s_or_b64 exec, exec, s[4:5]
	v_cvt_f32_u32_e32 v5, v3
	s_waitcnt vmcnt(0)
	v_readfirstlane_b32 s4, v4
	v_sub_u32_e32 v4, 0, v3
	v_rcp_iflag_f32_e32 v5, v5
	v_add_u32_e32 v6, s4, v0
	v_mul_f32_e32 v5, 0x4f7ffffe, v5
	v_cvt_u32_f32_e32 v5, v5
	v_mul_lo_u32 v0, v4, v5
	v_mul_hi_u32 v0, v5, v0
	v_add_u32_e32 v0, v5, v0
	v_mul_hi_u32 v0, v6, v0
	v_mul_lo_u32 v4, v0, v3
	v_sub_u32_e32 v4, v6, v4
	v_add_u32_e32 v5, 1, v0
	v_cmp_ge_u32_e32 vcc, v4, v3
	s_nop 1
	v_cndmask_b32_e32 v0, v0, v5, vcc
	v_sub_u32_e32 v5, v4, v3
	v_cndmask_b32_e32 v4, v4, v5, vcc
	v_add_u32_e32 v5, 1, v0
	v_cmp_ge_u32_e32 vcc, v4, v3
	v_add_u32_e32 v4, 1, v6
	s_nop 0
	v_cndmask_b32_e32 v0, v0, v5, vcc
	v_mul_lo_u32 v5, v3, v0
	v_add_u32_e32 v3, v5, v3
	v_cmp_ne_u32_e32 vcc, v4, v3
	s_and_saveexec_b64 s[4:5], vcc
	s_xor_b64 s[4:5], exec, s[4:5]
	s_cbranch_execz .LBB0_1109
	v_cmp_eq_u32_e32 vcc, v6, v5
	s_and_saveexec_b64 s[6:7], vcc
	s_cbranch_execz .Lwb_skip
	buffer_wbl2 sc1
.Lwb_skip:
	s_or_b64 exec, exec, s[6:7]
	v_readlane_b32 s6, v253, 20
	v_readlane_b32 s7, v253, 21
	s_waitcnt lgkmcnt(0)
	s_nop 3
	global_load_dword v2, v1, s[6:7] sc1
	s_waitcnt vmcnt(0)
	v_cmp_eq_u32_e32 vcc, v2, v0
	s_and_saveexec_b64 s[6:7], vcc
	s_cbranch_execz .LBB0_1108
	s_mov_b32 s18, 1
	s_mov_b64 s[8:9], 0
	s_branch .LBB0_1095

; __global__ void __launch_bounds__(512, 2) mk_fwd(Args a_) {
;     ...
;         if (ph + 1 < ph_hi) { if (ph >= 1000) grid.sync(); else xcd_barrier(xbar); }
;     }
; }
.Lpost_getpc0:
	s_add_u32 s98, s98, (.LBB0_7-.Lpost_getpc0)&4294967295
	s_addc_u32 s99, s99, (.LBB0_7-.Lpost_getpc0)>>32
	s_setpc_b64 s[98:99]
	s_nop 0
	s_nop 0
	s_nop 0
	s_nop 0
	s_nop 0
	s_nop 0
	s_nop 0
	s_nop 0
	s_nop 0
	s_nop 0
	s_nop 0
	s_nop 0
	s_nop 0
	s_nop 0
	s_nop 0
	s_nop 0
	s_nop 0
	s_nop 0
	s_nop 0
	s_nop 0
	s_nop 0
	s_nop 0
	s_nop 0
	s_nop 0
	s_nop 0
	s_nop 0
	s_nop 0
	s_nop 0
	s_nop 0
	s_nop 0
	s_nop 0
	s_nop 0
	s_nop 0
	s_nop 0
	s_nop 0
	s_nop 0
	s_nop 0
	s_nop 0
	s_nop 0
	s_nop 0
	s_nop 0
	s_nop 0
	s_nop 0
	s_nop 0
	s_nop 0
	s_nop 0
	s_nop 0
	s_nop 0
	s_nop 0
	s_nop 0
	s_nop 0
	s_nop 0
	s_nop 0
	s_nop 0
	s_nop 0
	s_nop 0
	s_nop 0
	s_nop 0
	s_nop 0
	s_nop 0
	s_nop 0
	s_nop 0
	s_nop 0
	s_nop 0
	s_nop 0
	s_nop 0
	s_nop 0
	s_nop 0
	s_nop 0
	s_nop 0
	s_nop 0
	s_nop 0
	s_nop 0
	s_nop 0
	s_nop 0
	s_nop 0
	s_nop 0
	s_nop 0
	s_nop 0
	s_nop 0
	s_nop 0
	s_nop 0
	s_nop 0
	s_nop 0
	s_nop 0
	s_nop 0
	s_nop 0
	s_nop 0
	s_nop 0
	s_nop 0
	s_nop 0
	s_nop 0
	s_nop 0
	s_nop 0
	s_nop 0
	s_nop 0
	s_nop 0
	s_nop 0
	s_nop 0
	s_nop 0
	s_nop 0
	s_nop 0
	s_nop 0
	s_nop 0
	s_nop 0
	s_nop 0
	s_nop 0
	s_nop 0
	s_nop 0
	s_nop 0
	s_nop 0
	s_nop 0
	s_nop 0
	s_nop 0
	s_nop 0
	s_nop 0
	s_nop 0
	s_nop 0
	s_nop 0
	s_nop 0
	s_nop 0
	s_nop 0
	s_nop 0
	s_nop 0
	s_nop 0
	s_nop 0
	s_nop 0
	s_nop 0
	s_nop 0
	s_nop 0
	s_nop 0
	s_nop 0
	s_nop 0
	s_nop 0
	s_nop 0
	s_nop 0
	s_nop 0
	s_nop 0
	s_nop 0
	s_nop 0
	s_nop 0
	s_nop 0
	s_nop 0
	s_nop 0
	s_nop 0
	s_nop 0
	s_nop 0
	s_nop 0
	s_nop 0
	s_nop 0
	s_nop 0
	s_nop 0
	s_nop 0
	s_nop 0
	s_nop 0
	s_nop 0
	s_nop 0
	s_nop 0
	s_nop 0
	s_nop 0
	s_nop 0
	s_nop 0
	s_nop 0
	s_nop 0
	s_nop 0
	s_nop 0
	s_nop 0
	s_nop 0
	s_nop 0
	s_nop 0
	s_nop 0
	s_nop 0
	s_nop 0
	s_nop 0
	s_nop 0
	s_nop 0
	s_nop 0
	s_nop 0
	s_nop 0
	s_nop 0
	s_nop 0
	s_nop 0
	s_nop 0
	s_nop 0
	s_nop 0
	s_nop 0
	s_nop 0
	s_nop 0
	s_nop 0
	s_nop 0
	s_nop 0
	s_nop 0
	s_nop 0
	s_nop 0
	s_nop 0
	s_nop 0
	s_nop 0
	s_nop 0
	s_nop 0
	s_nop 0
	s_nop 0
	s_nop 0
	s_nop 0
	s_nop 0
	s_nop 0
	s_nop 0
	s_nop 0
	s_nop 0
	s_nop 0
	s_nop 0
	s_nop 0
	s_nop 0
	s_nop 0
	s_nop 0
	s_nop 0
	s_nop 0
	s_nop 0
	s_nop 0
	s_nop 0
	s_nop 0
	s_nop 0
	s_nop 0
	s_nop 0
	s_nop 0
	s_nop 0
	s_nop 0
	s_nop 0
	s_nop 0
	s_nop 0
	s_nop 0
	s_nop 0
	s_nop 0
	s_nop 0
	s_nop 0
	s_nop 0
	s_nop 0
	s_nop 0
	s_nop 0
	s_nop 0
	s_nop 0
	s_nop 0
	s_nop 0
	s_nop 0
	s_nop 0
	s_nop 0
	s_nop 0
	s_nop 0
	s_nop 0
	s_nop 0
	s_nop 0
	s_nop 0
	s_nop 0
	s_nop 0
	s_nop 0
	s_nop 0
	s_nop 0
	s_nop 0
	s_nop 0
	s_nop 0
	s_nop 0
	s_nop 0
	s_nop 0
	s_nop 0
	s_nop 0
	s_nop 0
	s_nop 0
	s_nop 0
	s_nop 0
	s_nop 0
	s_nop 0
	s_nop 0
	s_nop 0
	s_nop 0
	s_nop 0
	s_nop 0
	s_nop 0
	s_nop 0
	s_nop 0
	s_nop 0
	s_nop 0
	s_nop 0
	s_nop 0
	s_nop 0
	s_nop 0
	s_nop 0
	s_nop 0
	s_nop 0
	s_nop 0
	s_nop 0
	s_nop 0
	s_nop 0
	s_nop 0
	s_nop 0
	s_nop 0
	s_nop 0
	s_nop 0
	s_nop 0
	s_nop 0
	s_nop 0
	s_nop 0
	s_nop 0
	s_nop 0
	s_nop 0
	s_nop 0
	s_nop 0
	s_nop 0
	s_nop 0
	s_nop 0
	s_nop 0
	s_nop 0
	s_nop 0
	s_nop 0
	s_nop 0
	s_nop 0
	s_nop 0
	s_nop 0
	s_nop 0
	s_nop 0
	s_nop 0
	s_nop 0
	s_nop 0
	s_nop 0
	s_nop 0
	s_nop 0
	s_nop 0
	s_nop 0
	s_nop 0
	s_nop 0
	s_nop 0
	s_nop 0
	s_nop 0
	s_nop 0
	s_nop 0
	s_nop 0
	s_nop 0
	s_nop 0
	s_nop 0
	s_nop 0
	s_nop 0
	s_nop 0
	s_nop 0
	s_nop 0
	s_nop 0
	s_nop 0
	s_nop 0
	s_nop 0
	s_nop 0
	s_nop 0
	s_nop 0
	s_nop 0
	s_nop 0
	s_nop 0
	s_nop 0
	s_nop 0
	s_nop 0
	s_nop 0
	s_nop 0
	s_nop 0
	s_nop 0
	s_nop 0
	s_nop 0
	s_nop 0
	s_nop 0
	s_nop 0
	s_nop 0
	s_nop 0
	s_nop 0
	s_nop 0
	s_nop 0
	s_nop 0
	s_nop 0
	s_nop 0
	s_nop 0
	s_nop 0
	s_nop 0
	s_nop 0
	s_nop 0
	s_nop 0
	s_nop 0
	s_nop 0
	s_nop 0
	s_nop 0
	s_nop 0
	s_nop 0
	s_nop 0
	s_nop 0
	s_nop 0
	s_nop 0
	s_nop 0
	s_nop 0
	s_nop 0
	s_nop 0
	s_nop 0
	s_nop 0
	s_nop 0
	s_nop 0
	s_nop 0
	s_nop 0
	s_nop 0
	s_nop 0
	s_nop 0
	s_nop 0
	s_nop 0
	s_nop 0
	s_nop 0
	s_nop 0
	s_nop 0
	s_nop 0
	s_nop 0
	s_nop 0
	s_nop 0
	s_nop 0
	s_nop 0
	s_nop 0
	s_nop 0
	s_nop 0
	s_nop 0
	s_nop 0
	s_nop 0
	s_nop 0
	s_nop 0
	s_nop 0
	s_nop 0
	s_nop 0
	s_nop 0
	s_nop 0
	s_nop 0
	s_nop 0
	s_nop 0
	s_nop 0
	s_nop 0
	s_nop 0
	s_nop 0
	s_nop 0
	s_nop 0
	s_nop 0
	s_nop 0
	s_nop 0
	s_nop 0
	s_nop 0
	s_nop 0
	s_nop 0
	s_nop 0
	s_nop 0
	s_nop 0
	s_nop 0
	s_nop 0
	s_nop 0
	s_nop 0
	s_nop 0
	s_nop 0
	s_nop 0
	s_nop 0
	s_nop 0
	s_nop 0
	s_nop 0
	s_nop 0
	s_nop 0
	s_nop 0
	s_nop 0
	s_nop 0
	s_nop 0
	s_nop 0
	s_nop 0
	s_nop 0
	s_nop 0
	s_nop 0
	s_nop 0
	s_nop 0
	s_nop 0
	s_nop 0
	s_nop 0
	s_nop 0
	s_nop 0
	s_nop 0
	s_nop 0
	s_nop 0
	s_nop 0
	s_nop 0
	s_nop 0
	s_nop 0
	s_nop 0
	s_nop 0
	s_nop 0
	s_nop 0
	s_nop 0
	s_nop 0
	s_nop 0
	s_nop 0
	s_nop 0
	s_nop 0
	s_nop 0
	s_nop 0
.LBB0_1140:
	s_endpgm
